# sc1-store/sc1-load protocol for the row partial sums in the fused epilogue (no wbl2/inv) + waves 4-7 delayed 384 cycles per key tile in attention
# baseline (speedup 1.0000x reference)
_Z4mega6Paramsii:
	s_mov_b32 s16, s2
	s_load_dwordx16 s[36:51], s[0:1], 0x0
	s_load_dwordx8 s[20:27], s[0:1], 0x80
	s_load_dword s2, s[0:1], 0xb0
	s_load_dwordx2 s[90:91], s[0:1], 0xa8
	s_add_u32 s4, s0, 0xa8
	v_and_b32_e32 v194, 0x3ff, v0
	s_addc_u32 s5, s1, 0
	v_cmp_eq_u32_e64 s[14:15], 0, v194
	v_readfirstlane_b32 s99, v194
	s_waitcnt lgkmcnt(0)
	v_writelane_b32 v242, s2, 0
	s_cmp_lt_u32 s16, 0x80
	s_cbranch_scc0 .Lf11_zskip
	s_lshl_b32 s2, s16, 7
	s_add_u32 s6, s26, 0x3c08000
	s_addc_u32 s7, s27, 0
	s_add_u32 s6, s6, s2
	s_addc_u32 s7, s7, 0
	v_mov_b32_e32 v1, 0
	s_and_saveexec_b64 s[2:3], s[14:15]
	global_store_dword v1, v1, s[6:7]
	s_or_b64 exec, exec, s[2:3]

.LBB0_364:
	s_and_saveexec_b64 s[0:1], s[2:3]
	s_nop 2
	v_mov_b32_e32 v32, s59
	v_mov_b32_e32 v33, s17
	ds_write_b32 v32, v33 offset:40960
	s_or_b64 exec, exec, s[0:1]
	s_waitcnt lgkmcnt(0)
	s_barrier
	s_waitcnt vmcnt(3)
	ds_write_b128 v164, v[80:83]
	s_waitcnt vmcnt(2)
	ds_write_b128 v164, v[84:87] offset:18432
	s_waitcnt vmcnt(1)
	ds_write_b128 v166, v[88:91]
	s_waitcnt vmcnt(0)
	ds_write_b128 v166, v[92:95] offset:18432
	ds_read_b128 v[32:35], v129 offset:40960
	ds_read_b128 v[36:39], v129 offset:40976
	s_mov_b64 s[0:1], -1
	s_waitcnt lgkmcnt(0)
	s_barrier
	s_cselect_b32 s100, 1, 0
	s_cmp_lt_u32 s99, 0x100
	s_cbranch_scc1 .Lstg_3
	s_sleep 6
.Lstg_3:
	s_cmp_lg_u32 s100, 0
	v_and_b32_e32 v32, v32, v33
	v_and_b32_e32 v32, v32, v34
	v_and_b32_e32 v32, v32, v35
	v_and_b32_e32 v32, v32, v36
	v_and_b32_e32 v32, v32, v37
	v_and_b32_e32 v32, v32, v38
	v_and_b32_e32 v32, v32, v39
	v_and_b32_e32 v32, 1, v32
	v_cmp_eq_u32_e32 vcc, 1, v32
	s_cbranch_vccz .LBB0_368
	s_and_b64 vcc, exec, s[0:1]
	s_cbranch_vccz .LBB0_364
	s_branch .LBB0_443

.LBB0_392:
	s_and_saveexec_b64 s[0:1], s[2:3]
	s_nop 4
	v_mov_b32_e32 v32, s59
	v_mov_b32_e32 v33, s17
	ds_write_b32 v32, v33 offset:40960
	s_or_b64 exec, exec, s[0:1]
	s_waitcnt lgkmcnt(0)
	s_barrier
	s_waitcnt vmcnt(3)
	ds_write_b128 v164, v[100:103]
	s_waitcnt vmcnt(2)
	ds_write_b128 v164, v[96:99] offset:18432
	s_waitcnt vmcnt(1)
	ds_write_b128 v166, v[108:111]
	s_waitcnt vmcnt(0)
	ds_write_b128 v166, v[104:107] offset:18432
	ds_read_b128 v[32:35], v129 offset:40960
	ds_read_b128 v[36:39], v129 offset:40976
	s_mov_b64 s[0:1], -1
	s_waitcnt lgkmcnt(0)
	s_barrier
	s_cselect_b32 s100, 1, 0
	s_cmp_lt_u32 s99, 0x100
	s_cbranch_scc1 .Lstg_2
	s_sleep 6

.LBB0_447:
	s_lshl_b32 s59, s57, 7
	s_cmp_lt_u32 s57, 2
	s_barrier
	s_waitcnt vmcnt(3)
	ds_write_b128 v200, v[80:83]
	s_waitcnt vmcnt(2)
	ds_write_b128 v200, v[84:87] offset:18432
	s_waitcnt vmcnt(1)
	ds_write_b128 v201, v[88:91]
	s_waitcnt vmcnt(0)
	ds_write_b128 v201, v[92:95] offset:18432
	s_waitcnt lgkmcnt(0)
	s_barrier
	s_cselect_b32 s100, 1, 0
	s_cmp_lt_u32 s99, 0x100
	s_cbranch_scc1 .Lstg_1
	s_sleep 6
.Lstg_1:
	s_cmp_lg_u32 s100, 0
	s_cbranch_scc1 .LBB0_449
	s_add_i32 s0, s59, 0xffffff00
	v_add_u32_e32 v32, s0, v198
	v_ashrrev_i32_e32 v33, 31, v32
	v_lshlrev_b64 v[32:33], 7, v[32:33]
	v_lshl_add_u64 v[34:35], v[166:167], 0, v[32:33]
	v_lshl_add_u64 v[32:33], v[168:169], 0, v[32:33]
	global_load_dwordx4 v[80:83], v[34:35], off
	global_load_dwordx4 v[84:87], v[32:33], off
	v_add_u32_e32 v32, s0, v199
	v_ashrrev_i32_e32 v33, 31, v32
	v_lshlrev_b64 v[32:33], 7, v[32:33]
	v_lshl_add_u64 v[34:35], v[170:171], 0, v[32:33]
	v_lshl_add_u64 v[32:33], v[172:173], 0, v[32:33]
	global_load_dwordx4 v[88:91], v[34:35], off
	global_load_dwordx4 v[92:95], v[32:33], off

.LBB0_484:
	s_cmp_lt_u32 s57, 3
	s_barrier
	s_waitcnt vmcnt(3)
	ds_write_b128 v200, v[96:99]
	s_waitcnt vmcnt(2)
	ds_write_b128 v200, v[100:103] offset:18432
	s_waitcnt vmcnt(1)
	ds_write_b128 v201, v[104:107]
	s_waitcnt vmcnt(0)
	ds_write_b128 v201, v[108:111] offset:18432
	s_waitcnt lgkmcnt(0)
	s_barrier
	s_cselect_b32 s100, 1, 0
	s_cmp_lt_u32 s99, 0x100
	s_cbranch_scc1 .Lstg_0
	s_sleep 6
.Lstg_0:
	s_cmp_lg_u32 s100, 0
	s_cbranch_scc1 .LBB0_486
	s_add_i32 s0, s59, 0xfffffe80
	v_add_u32_e32 v32, s0, v198
	v_ashrrev_i32_e32 v33, 31, v32
	v_lshlrev_b64 v[32:33], 7, v[32:33]
	v_lshl_add_u64 v[34:35], v[166:167], 0, v[32:33]
	v_lshl_add_u64 v[32:33], v[168:169], 0, v[32:33]
	global_load_dwordx4 v[96:99], v[34:35], off
	global_load_dwordx4 v[100:103], v[32:33], off
	v_add_u32_e32 v32, s0, v199
	v_ashrrev_i32_e32 v33, 31, v32
	v_lshlrev_b64 v[32:33], 7, v[32:33]
	v_lshl_add_u64 v[34:35], v[170:171], 0, v[32:33]
	v_lshl_add_u64 v[32:33], v[172:173], 0, v[32:33]
	global_load_dwordx4 v[104:107], v[34:35], off
	global_load_dwordx4 v[108:111], v[32:33], off

	.amdhsa_kernel _Z4mega6Paramsii
		.amdhsa_group_segment_fixed_size 0
		.amdhsa_private_segment_fixed_size 0
		.amdhsa_kernarg_size 424
		.amdhsa_user_sgpr_count 2
		.amdhsa_user_sgpr_dispatch_ptr 0
		.amdhsa_user_sgpr_queue_ptr 0
		.amdhsa_user_sgpr_kernarg_segment_ptr 1
		.amdhsa_user_sgpr_dispatch_id 0
		.amdhsa_user_sgpr_kernarg_preload_length 0
		.amdhsa_user_sgpr_kernarg_preload_offset 0
		.amdhsa_user_sgpr_private_segment_size 0
		.amdhsa_uses_dynamic_stack 0
		.amdhsa_enable_private_segment 0
		.amdhsa_system_sgpr_workgroup_id_x 1
		.amdhsa_system_sgpr_workgroup_id_y 0
		.amdhsa_system_sgpr_workgroup_id_z 0
		.amdhsa_system_sgpr_workgroup_info 0
		.amdhsa_system_vgpr_workitem_id 2
		.amdhsa_next_free_vgpr 243
		.amdhsa_next_free_sgpr 101
		.amdhsa_accum_offset 244
		.amdhsa_reserve_vcc 1
		.amdhsa_float_round_mode_32 0
		.amdhsa_float_round_mode_16_64 0
		.amdhsa_float_denorm_mode_32 3
		.amdhsa_float_denorm_mode_16_64 3
		.amdhsa_dx10_clamp 1
		.amdhsa_ieee_mode 1
		.amdhsa_fp16_overflow 0
		.amdhsa_tg_split 0
		.amdhsa_exception_fp_ieee_invalid_op 0
		.amdhsa_exception_fp_denorm_src 0
		.amdhsa_exception_fp_ieee_div_zero 0
		.amdhsa_exception_fp_ieee_overflow 0
		.amdhsa_exception_fp_ieee_underflow 0
		.amdhsa_exception_fp_ieee_inexact 0
		.amdhsa_exception_int_div_zero 0
	.end_amdhsa_kernel

amdhsa.kernels:
  - .agpr_count:     0
    .args:
      - .offset:         0
        .size:           160
        .value_kind:     by_value
      - .offset:         160
        .size:           4
        .value_kind:     by_value
      - .offset:         164
        .size:           4
        .value_kind:     by_value
      - .offset:         168
        .size:           4
        .value_kind:     hidden_block_count_x
      - .offset:         172
        .size:           4
        .value_kind:     hidden_block_count_y
      - .offset:         176
        .size:           4
        .value_kind:     hidden_block_count_z
      - .offset:         180
        .size:           2
        .value_kind:     hidden_group_size_x
      - .offset:         182
        .size:           2
        .value_kind:     hidden_group_size_y
      - .offset:         184
        .size:           2
        .value_kind:     hidden_group_size_z
      - .offset:         186
        .size:           2
        .value_kind:     hidden_remainder_x
      - .offset:         188
        .size:           2
        .value_kind:     hidden_remainder_y
      - .offset:         190
        .size:           2
        .value_kind:     hidden_remainder_z
      - .offset:         208
        .size:           8
        .value_kind:     hidden_global_offset_x
      - .offset:         216
        .size:           8
        .value_kind:     hidden_global_offset_y
      - .offset:         224
        .size:           8
        .value_kind:     hidden_global_offset_z
      - .offset:         232
        .size:           2
        .value_kind:     hidden_grid_dims
      - .offset:         256
        .size:           8
        .value_kind:     hidden_multigrid_sync_arg
      - .offset:         288
        .size:           4
        .value_kind:     hidden_dynamic_lds_size
    .group_segment_fixed_size: 0
    .kernarg_segment_align: 8
    .kernarg_segment_size: 424
    .language:       OpenCL C
    .language_version:
      - 2
      - 0
    .max_flat_workgroup_size: 512
    .name:           _Z4mega6Paramsii
    .private_segment_fixed_size: 0
    .sgpr_count:     107
    .sgpr_spill_count: 3
    .symbol:         _Z4mega6Paramsii.kd
    .uniform_work_group_size: 1
    .uses_dynamic_stack: false
    .vgpr_count:     243
    .vgpr_spill_count: 0
    .wavefront_size: 64
